# main LayerNorm walks the prompt rows in descending order so it reads the Z rows G2 wrote last while they are still in the Infinity Cache
# speedup vs baseline: 1.0036x; 1.0036x over previous
.LBB0_1433:
	v_readlane_b32 s1, v254, 39
	s_add_i32 s1, s1, s0
	s_sub_i32 s4, s1, 32
	s_ashr_i32 s1, s0, 31
	s_xor_b32 s8, s0, 0xffff
	s_mov_b32 s9, 0
	s_lshl_b64 s[8:9], s[8:9], 11
	s_cmp_lt_i32 s4, 0x10000
	s_cselect_b64 s[6:7], -1, 0
	s_and_b64 s[10:11], s[6:7], exec
	s_cselect_b32 s10, s4, s0
	s_ashr_i32 s11, s10, 31
	s_xor_b32 s10, s10, 0xffff
	s_lshl_b64 s[10:11], s[10:11], 11
	s_waitcnt vmcnt(1)
	v_lshl_add_u64 v[34:35], v[58:59], 0, s[8:9]
	s_waitcnt vmcnt(0)
	v_lshl_add_u64 v[38:39], v[58:59], 0, s[10:11]
	global_load_dwordx4 v[50:53], v[34:35], off
	global_load_dwordx4 v[44:47], v[34:35], off offset:1024
	s_nop 0
	global_load_dwordx4 v[34:37], v[38:39], off
	s_nop 0
	global_load_dwordx4 v[38:41], v[38:39], off offset:1024
	s_mov_b64 s[10:11], -1
	s_waitcnt vmcnt(3)
	v_and_b32_e32 v75, 0xffff0000, v51
	s_waitcnt vmcnt(2)
	v_lshlrev_b32_e32 v56, 16, v46
	v_and_b32_e32 v66, 0xffff0000, v46
	v_lshlrev_b32_e32 v54, 16, v47
	v_and_b32_e32 v64, 0xffff0000, v47
	v_lshlrev_b32_e32 v47, 16, v51
	v_lshlrev_b32_e32 v46, 16, v50
	v_and_b32_e32 v74, 0xffff0000, v50
	v_pk_add_f32 v[48:49], v[46:47], v[74:75]
	v_lshlrev_b32_e32 v51, 16, v53
	v_lshlrev_b32_e32 v50, 16, v52
	v_and_b32_e32 v77, 0xffff0000, v53
	v_and_b32_e32 v76, 0xffff0000, v52
	v_add_f32_e32 v0, v48, v49
	v_pk_add_f32 v[48:49], v[50:51], v[76:77]
	v_lshlrev_b32_e32 v42, 16, v44
	v_and_b32_e32 v43, 0xffff0000, v44
	v_lshlrev_b32_e32 v44, 16, v45
	v_and_b32_e32 v45, 0xffff0000, v45
	v_pk_add_f32 v[48:49], v[48:49], v[48:49] op_sel_hi:[0,1]
	v_add_f32_e32 v65, 0, v0
	v_add_f32_e32 v57, v42, v43
	v_add_f32_e32 v67, v44, v45
	v_mov_b32_e32 v55, v49
	v_pk_add_f32 v[52:53], v[56:57], v[66:67]
	v_pk_add_f32 v[48:49], v[54:55], v[64:65]
	s_nop 0
	v_pk_add_f32 v[48:49], v[52:53], v[48:49]
	s_nop 0
	v_add_f32_e32 v0, v48, v49
	ds_bpermute_b32 v48, v68, v0
	s_waitcnt lgkmcnt(0)
	v_add_f32_e32 v0, v0, v48
	ds_bpermute_b32 v48, v69, v0
	s_waitcnt lgkmcnt(0)
	v_add_f32_e32 v0, v0, v48
	ds_bpermute_b32 v48, v70, v0
	s_waitcnt lgkmcnt(0)
	v_add_f32_e32 v0, v0, v48
	ds_bpermute_b32 v48, v71, v0
	s_waitcnt lgkmcnt(0)
	v_add_f32_e32 v0, v0, v48
	ds_bpermute_b32 v48, v72, v0
	s_waitcnt lgkmcnt(0)
	v_add_f32_e32 v0, v0, v48
	ds_bpermute_b32 v48, v73, v0
	s_waitcnt lgkmcnt(0)
	v_add_f32_e32 v55, v0, v48
	v_fmac_f32_e32 v74, 0xba800000, v55
	v_fmac_f32_e32 v75, 0xba800000, v55
	v_fmac_f32_e32 v47, 0xba800000, v55
	v_fmac_f32_e32 v46, 0xba800000, v55
	v_mov_b32_e32 v48, v47
	v_mov_b32_e32 v49, v75
	v_mov_b32_e32 v47, v74
	v_pk_mul_f32 v[52:53], v[48:49], v[48:49]
	v_pk_mul_f32 v[74:75], v[46:47], v[46:47]
	v_fmac_f32_e32 v76, 0xba800000, v55
	v_pk_mov_b32 v[78:79], v[74:75], v[52:53] op_sel:[1,0]
	v_mov_b32_e32 v75, v53
	v_fmac_f32_e32 v77, 0xba800000, v55
	v_fmac_f32_e32 v51, 0xba800000, v55
	v_pk_add_f32 v[52:53], v[78:79], v[74:75]
	v_fmac_f32_e32 v50, 0xba800000, v55
	v_mov_b32_e32 v74, v51
	v_mov_b32_e32 v75, v77
	v_mov_b32_e32 v51, v76
	v_pk_mul_f32 v[78:79], v[74:75], v[74:75]
	v_pk_mul_f32 v[76:77], v[50:51], v[50:51]
	v_fmac_f32_e32 v42, 0xba800000, v55
	v_pk_mov_b32 v[80:81], v[76:77], v[78:79] op_sel:[1,0]
	v_mov_b32_e32 v77, v79
	v_fmac_f32_e32 v43, 0xba800000, v55
	v_fmac_f32_e32 v44, 0xba800000, v55
	v_mul_f32_e32 v0, v42, v42
	v_pk_add_f32 v[76:77], v[80:81], v[76:77]
	v_fmac_f32_e32 v45, 0xba800000, v55
	v_pk_fma_f32 v[78:79], v[42:43], v[42:43], v[0:1] op_sel_hi:[1,1,0]
	v_mul_f32_e32 v0, v44, v44
	v_pk_add_f32 v[52:53], v[52:53], v[52:53] op_sel_hi:[0,1]
	v_pk_add_f32 v[76:77], v[76:77], v[76:77] op_sel_hi:[0,1]
	v_pk_fma_f32 v[80:81], v[44:45], v[44:45], v[0:1] op_sel_hi:[1,1,0]
	v_fmac_f32_e32 v64, 0xba800000, v55
	v_fmac_f32_e32 v54, 0xba800000, v55
	v_fmac_f32_e32 v66, 0xba800000, v55
	v_fmac_f32_e32 v56, 0xba800000, v55
	v_mul_f32_e32 v78, v56, v56
	v_mul_f32_e32 v80, v66, v66
	v_mul_f32_e32 v52, v54, v54
	v_mul_f32_e32 v76, v64, v64
	v_pk_add_f32 v[78:79], v[78:79], v[80:81]
	v_pk_add_f32 v[52:53], v[52:53], v[76:77]
	v_mov_b32_e32 v57, v66
	v_pk_add_f32 v[52:53], v[78:79], v[52:53]
	v_mov_b32_e32 v55, v64
	v_add_f32_e32 v0, v52, v53
	ds_bpermute_b32 v52, v68, v0
	s_waitcnt lgkmcnt(0)
	v_add_f32_e32 v0, v0, v52
	ds_bpermute_b32 v52, v69, v0
	s_waitcnt lgkmcnt(0)
	v_add_f32_e32 v0, v0, v52
	ds_bpermute_b32 v52, v70, v0
	s_waitcnt lgkmcnt(0)
	v_add_f32_e32 v0, v0, v52
	ds_bpermute_b32 v52, v71, v0
	s_waitcnt lgkmcnt(0)
	v_add_f32_e32 v0, v0, v52
	ds_bpermute_b32 v52, v72, v0
	s_waitcnt lgkmcnt(0)
	v_add_f32_e32 v0, v0, v52
	ds_bpermute_b32 v52, v73, v0
	s_waitcnt lgkmcnt(0)
	v_add_f32_e32 v0, v0, v52
	v_fmamk_f32 v0, v0, 0x3a800000, v227
	v_cmp_gt_f32_e32 vcc, s86, v0
	v_mul_f32_e32 v52, 0x4b800000, v0
	s_nop 0
	v_cndmask_b32_e32 v0, v0, v52, vcc
	v_rsq_f32_e32 v0, v0
	s_nop 0
	v_mul_f32_e32 v52, 0x45800000, v0
	v_cndmask_b32_e32 v0, v0, v52, vcc
	v_pk_mul_f32 v[46:47], v[46:47], v[0:1] op_sel_hi:[1,0]
	v_pk_mul_f32 v[48:49], v[48:49], v[0:1] op_sel_hi:[1,0]
	v_pk_mul_f32 v[50:51], v[50:51], v[0:1] op_sel_hi:[1,0]
	v_pk_mul_f32 v[52:53], v[74:75], v[0:1] op_sel_hi:[1,0]
	v_pk_mul_f32 v[42:43], v[42:43], v[0:1] op_sel_hi:[1,0]
	v_pk_mul_f32 v[44:45], v[44:45], v[0:1] op_sel_hi:[1,0]
	v_pk_mul_f32 v[66:67], v[56:57], v[0:1] op_sel_hi:[1,0]
	v_pk_mul_f32 v[54:55], v[54:55], v[0:1] op_sel_hi:[1,0]
	v_pk_fma_f32 v[48:49], v[8:9], v[48:49], v[16:17]
	v_pk_fma_f32 v[46:47], v[6:7], v[46:47], v[14:15]
	v_pk_fma_f32 v[52:53], v[4:5], v[52:53], v[12:13]
	v_pk_fma_f32 v[50:51], v[2:3], v[50:51], v[10:11]
	v_pk_fma_f32 v[44:45], v[24:25], v[44:45], v[32:33]
	v_pk_fma_f32 v[42:43], v[22:23], v[42:43], v[30:31]
	v_pk_fma_f32 v[56:57], v[20:21], v[54:55], v[28:29]
	v_pk_fma_f32 v[54:55], v[18:19], v[66:67], v[26:27]
	s_and_b64 vcc, exec, s[20:21]
	s_cbranch_vccz .LBB0_1436
	s_xor_b32 s10, s0, 0xffff
	s_mov_b32 s11, 0
	s_lshl_b64 s[10:11], s[10:11], 12
	v_lshl_add_u64 v[64:65], v[62:63], 0, s[10:11]
	global_store_dwordx4 v[64:65], v[46:49], off nt
	global_store_dwordx4 v[64:65], v[50:53], off offset:16 nt
	global_store_dwordx4 v[64:65], v[42:45], off offset:2048 nt
	global_store_dwordx4 v[64:65], v[54:57], off offset:2064 nt
	s_cbranch_execz .LBB0_1437

.LBB0_1438:
	s_waitcnt vmcnt(0)
	v_lshlrev_b32_e32 v42, 16, v38
	v_and_b32_e32 v43, 0xffff0000, v38
	v_lshlrev_b32_e32 v44, 16, v39
	v_and_b32_e32 v45, 0xffff0000, v39
	v_lshlrev_b32_e32 v39, 16, v35
	v_lshlrev_b32_e32 v38, 16, v34
	v_and_b32_e32 v35, 0xffff0000, v35
	v_and_b32_e32 v34, 0xffff0000, v34
	v_lshlrev_b32_e32 v46, 16, v40
	v_and_b32_e32 v48, 0xffff0000, v40
	v_lshlrev_b32_e32 v50, 16, v41
	v_and_b32_e32 v52, 0xffff0000, v41
	v_pk_add_f32 v[40:41], v[38:39], v[34:35]
	v_add_f32_e32 v47, v42, v43
	v_add_f32_e32 v0, v40, v41
	v_lshlrev_b32_e32 v41, 16, v37
	v_lshlrev_b32_e32 v40, 16, v36
	v_and_b32_e32 v37, 0xffff0000, v37
	v_and_b32_e32 v36, 0xffff0000, v36
	v_pk_add_f32 v[54:55], v[40:41], v[36:37]
	v_add_f32_e32 v53, 0, v0
	v_pk_add_f32 v[54:55], v[54:55], v[54:55] op_sel_hi:[0,1]
	v_add_f32_e32 v49, v44, v45
	v_mov_b32_e32 v51, v55
	v_pk_add_f32 v[56:57], v[46:47], v[48:49]
	v_pk_add_f32 v[54:55], v[50:51], v[52:53]
	s_mov_b64 s[6:7], -1
	v_pk_add_f32 v[54:55], v[56:57], v[54:55]
	s_nop 0
	v_add_f32_e32 v0, v54, v55
	ds_bpermute_b32 v47, v68, v0
	s_waitcnt lgkmcnt(0)
	v_add_f32_e32 v0, v0, v47
	ds_bpermute_b32 v47, v69, v0
	s_waitcnt lgkmcnt(0)
	v_add_f32_e32 v0, v0, v47
	ds_bpermute_b32 v47, v70, v0
	s_waitcnt lgkmcnt(0)
	v_add_f32_e32 v0, v0, v47
	ds_bpermute_b32 v47, v71, v0
	s_waitcnt lgkmcnt(0)
	v_add_f32_e32 v0, v0, v47
	ds_bpermute_b32 v47, v72, v0
	s_waitcnt lgkmcnt(0)
	v_add_f32_e32 v0, v0, v47
	ds_bpermute_b32 v47, v73, v0
	s_waitcnt lgkmcnt(0)
	v_add_f32_e32 v47, v0, v47
	v_fmac_f32_e32 v34, 0xba800000, v47
	v_fmac_f32_e32 v35, 0xba800000, v47
	v_fmac_f32_e32 v39, 0xba800000, v47
	v_fmac_f32_e32 v38, 0xba800000, v47
	v_mov_b32_e32 v54, v39
	v_mov_b32_e32 v55, v35
	v_mov_b32_e32 v39, v34
	v_pk_mul_f32 v[56:57], v[54:55], v[54:55]
	v_pk_mul_f32 v[34:35], v[38:39], v[38:39]
	v_fmac_f32_e32 v36, 0xba800000, v47
	v_fmac_f32_e32 v37, 0xba800000, v47
	v_fmac_f32_e32 v41, 0xba800000, v47
	v_pk_mov_b32 v[64:65], v[34:35], v[56:57] op_sel:[1,0]
	v_mov_b32_e32 v35, v57
	v_fmac_f32_e32 v40, 0xba800000, v47
	v_mov_b32_e32 v56, v41
	v_mov_b32_e32 v57, v37
	v_mov_b32_e32 v41, v36
	v_pk_add_f32 v[34:35], v[64:65], v[34:35]
	v_pk_mul_f32 v[64:65], v[56:57], v[56:57]
	v_pk_mul_f32 v[36:37], v[40:41], v[40:41]
	v_fmac_f32_e32 v42, 0xba800000, v47
	v_pk_mov_b32 v[66:67], v[36:37], v[64:65] op_sel:[1,0]
	v_mov_b32_e32 v37, v65
	v_fmac_f32_e32 v43, 0xba800000, v47
	v_fmac_f32_e32 v44, 0xba800000, v47
	v_mul_f32_e32 v0, v42, v42
	v_pk_add_f32 v[36:37], v[66:67], v[36:37]
	v_fmac_f32_e32 v45, 0xba800000, v47
	v_pk_fma_f32 v[64:65], v[42:43], v[42:43], v[0:1] op_sel_hi:[1,1,0]
	v_mul_f32_e32 v0, v44, v44
	v_pk_add_f32 v[34:35], v[34:35], v[34:35] op_sel_hi:[0,1]
	v_pk_add_f32 v[36:37], v[36:37], v[36:37] op_sel_hi:[0,1]
	v_pk_fma_f32 v[66:67], v[44:45], v[44:45], v[0:1] op_sel_hi:[1,1,0]
	v_fmac_f32_e32 v52, 0xba800000, v47
	v_fmac_f32_e32 v50, 0xba800000, v47
	v_fmac_f32_e32 v48, 0xba800000, v47
	v_fmac_f32_e32 v46, 0xba800000, v47
	v_mul_f32_e32 v64, v46, v46
	v_mul_f32_e32 v66, v48, v48
	v_mul_f32_e32 v34, v50, v50
	v_mul_f32_e32 v36, v52, v52
	v_pk_add_f32 v[64:65], v[64:65], v[66:67]
	v_pk_add_f32 v[34:35], v[34:35], v[36:37]
	v_mov_b32_e32 v47, v48
	v_pk_add_f32 v[34:35], v[64:65], v[34:35]
	v_mov_b32_e32 v51, v52
	v_add_f32_e32 v0, v34, v35
	ds_bpermute_b32 v34, v68, v0
	s_waitcnt lgkmcnt(0)
	v_add_f32_e32 v0, v0, v34
	ds_bpermute_b32 v34, v69, v0
	s_waitcnt lgkmcnt(0)
	v_add_f32_e32 v0, v0, v34
	ds_bpermute_b32 v34, v70, v0
	s_waitcnt lgkmcnt(0)
	v_add_f32_e32 v0, v0, v34
	ds_bpermute_b32 v34, v71, v0
	s_waitcnt lgkmcnt(0)
	v_add_f32_e32 v0, v0, v34
	ds_bpermute_b32 v34, v72, v0
	s_waitcnt lgkmcnt(0)
	v_add_f32_e32 v0, v0, v34
	ds_bpermute_b32 v34, v73, v0
	s_waitcnt lgkmcnt(0)
	v_add_f32_e32 v0, v0, v34
	v_fmamk_f32 v0, v0, 0x3a800000, v227
	v_mul_f32_e32 v34, 0x4b800000, v0
	v_cmp_gt_f32_e32 vcc, s86, v0
	s_nop 1
	v_cndmask_b32_e32 v0, v0, v34, vcc
	v_rsq_f32_e32 v0, v0
	s_nop 0
	v_mul_f32_e32 v34, 0x45800000, v0
	v_cndmask_b32_e32 v0, v0, v34, vcc
	v_pk_mul_f32 v[34:35], v[38:39], v[0:1] op_sel_hi:[1,0]
	v_pk_mul_f32 v[36:37], v[54:55], v[0:1] op_sel_hi:[1,0]
	v_pk_mul_f32 v[38:39], v[40:41], v[0:1] op_sel_hi:[1,0]
	v_pk_mul_f32 v[40:41], v[56:57], v[0:1] op_sel_hi:[1,0]
	v_pk_mul_f32 v[42:43], v[42:43], v[0:1] op_sel_hi:[1,0]
	v_pk_mul_f32 v[44:45], v[44:45], v[0:1] op_sel_hi:[1,0]
	v_pk_mul_f32 v[46:47], v[46:47], v[0:1] op_sel_hi:[1,0]
	v_pk_mul_f32 v[48:49], v[50:51], v[0:1] op_sel_hi:[1,0]
	v_pk_fma_f32 v[36:37], v[8:9], v[36:37], v[16:17]
	v_pk_fma_f32 v[34:35], v[6:7], v[34:35], v[14:15]
	v_pk_fma_f32 v[40:41], v[4:5], v[40:41], v[12:13]
	v_pk_fma_f32 v[38:39], v[2:3], v[38:39], v[10:11]
	v_pk_fma_f32 v[44:45], v[24:25], v[44:45], v[32:33]
	v_pk_fma_f32 v[42:43], v[22:23], v[42:43], v[30:31]
	v_pk_fma_f32 v[48:49], v[20:21], v[48:49], v[28:29]
	v_pk_fma_f32 v[46:47], v[18:19], v[46:47], v[26:27]
	s_andn2_b64 vcc, exec, s[20:21]
	s_cbranch_vccnz .LBB0_1440
	s_xor_b32 s4, s4, 0xffff
	s_mov_b32 s5, 0
	s_lshl_b64 s[6:7], s[4:5], 12
	v_lshl_add_u64 v[50:51], v[62:63], 0, s[6:7]
	s_mov_b64 s[6:7], 0
	global_store_dwordx4 v[50:51], v[34:37], off nt
	global_store_dwordx4 v[50:51], v[38:41], off offset:16 nt
	global_store_dwordx4 v[50:51], v[42:45], off offset:2048 nt
	global_store_dwordx4 v[50:51], v[46:49], off offset:2064 nt
.LBB0_1440:
	s_andn2_b64 vcc, exec, s[6:7]
	s_cbranch_vccnz .LBB0_1432
	s_xor_b32 s4, s4, 0xffff
	s_mov_b32 s5, 0
	s_lshl_b64 s[4:5], s[4:5], 11
	v_lshl_add_u64 v[50:51], v[60:61], 0, s[4:5]
	v_cvt_pk_bf16_f32 v34, v34, v35
	v_cvt_pk_bf16_f32 v35, v36, v37
	v_cvt_pk_bf16_f32 v36, v38, v39
	v_cvt_pk_bf16_f32 v37, v40, v41
	global_store_dwordx4 v[50:51], v[34:37], off
	s_nop 1
	v_cvt_pk_bf16_f32 v34, v42, v43
	v_cvt_pk_bf16_f32 v35, v44, v45
	v_cvt_pk_bf16_f32 v36, v46, v47
	v_cvt_pk_bf16_f32 v37, v48, v49
	global_store_dwordx4 v[50:51], v[34:37], off offset:1024
	s_branch .LBB0_1432
